# attention: K/V stage store and two-ahead global prefetch issued before the step's last PV MFMAs (mask-free steps)
# speedup vs baseline: 1.0104x; 1.0104x over previous
.Lnd_107:
	s_and_b32 s33, s42, 1
	s_mul_i32 s6, s33, 0x9000
	v_add_u32_e32 v199, s6, v187
	v_add_u32_e32 v198, s6, v188
	s_mov_b64 s[54:55], exec
	v_readfirstlane_b32 s4, v186
	s_bitcmp1_b32 s4, 8
	s_cbranch_scc1 .Lab_B
	ds_read_b128 v[216:219], v199 offset:0
	ds_read_b128 v[232:235], v193 offset:0
	ds_read_b128 v[220:223], v199 offset:32
	ds_read_b128 v[236:239], v193 offset:32
	ds_read_b128 v[224:227], v199 offset:64
	ds_read_b128 v[244:247], v193 offset:64
	ds_read_b128 v[228:231], v199 offset:96
	ds_read_b128 v[248:251], v193 offset:96
	s_waitcnt lgkmcnt(6)
	v_mfma_f32_32x32x16_bf16 v[144:159], v[216:219], v[232:235], v[0:15]
	s_waitcnt lgkmcnt(4)
	v_mfma_f32_32x32x16_bf16 v[144:159], v[220:223], v[236:239], v[144:159]
	s_waitcnt lgkmcnt(2)
	v_mfma_f32_32x32x16_bf16 v[144:159], v[224:227], v[244:247], v[144:159]
	s_waitcnt lgkmcnt(0)
	v_mfma_f32_32x32x16_bf16 v[144:159], v[228:231], v[248:251], v[144:159]
	ds_read_b128 v[216:219], v199 offset:9216
	ds_read_b128 v[232:235], v193 offset:36864
	ds_read_b128 v[220:223], v199 offset:9248
	ds_read_b128 v[236:239], v193 offset:36896
	ds_read_b128 v[224:227], v199 offset:9280
	ds_read_b128 v[244:247], v193 offset:36928
	ds_read_b128 v[228:231], v199 offset:9312
	ds_read_b128 v[248:251], v193 offset:36960
	s_nop 3
	v_exp_f32_e32 v144, v144
	v_exp_f32_e32 v145, v145
	v_exp_f32_e32 v146, v146
	v_exp_f32_e32 v147, v147
	v_exp_f32_e32 v148, v148
	v_exp_f32_e32 v149, v149
	v_exp_f32_e32 v150, v150
	v_exp_f32_e32 v151, v151
	v_exp_f32_e32 v152, v152
	v_exp_f32_e32 v153, v153
	v_exp_f32_e32 v154, v154
	v_exp_f32_e32 v155, v155
	v_exp_f32_e32 v156, v156
	v_exp_f32_e32 v157, v157
	v_exp_f32_e32 v158, v158
	v_exp_f32_e32 v159, v159
	v_add_f32_e32 v243, v144, v145
	v_add_f32_e32 v243, v146, v243
	v_add_f32_e32 v243, v147, v243
	v_add_f32_e32 v243, v148, v243
	v_add_f32_e32 v243, v149, v243
	v_add_f32_e32 v243, v150, v243
	v_add_f32_e32 v243, v151, v243
	s_waitcnt lgkmcnt(6)
	v_mfma_f32_32x32x16_bf16 v[200:215], v[216:219], v[232:235], v[0:15]
	s_waitcnt lgkmcnt(4)
	v_mfma_f32_32x32x16_bf16 v[200:215], v[220:223], v[236:239], v[200:215]
	s_waitcnt lgkmcnt(2)
	v_mfma_f32_32x32x16_bf16 v[200:215], v[224:227], v[244:247], v[200:215]
	s_waitcnt lgkmcnt(0)
	v_mfma_f32_32x32x16_bf16 v[200:215], v[228:231], v[248:251], v[200:215]
	ds_read_b128 v[216:219], v198 offset:0
	ds_read_b128 v[224:227], v198 offset:4608
	ds_read_b128 v[232:235], v198 offset:9216
	ds_read_b128 v[244:247], v198 offset:13824
	ds_read_b128 v[220:223], v198 offset:32
	ds_read_b128 v[228:231], v198 offset:4640
	ds_read_b128 v[236:239], v198 offset:9248
	ds_read_b128 v[248:251], v198 offset:13856
	v_add_f32_e32 v243, v152, v243
	v_add_f32_e32 v243, v153, v243
	v_add_f32_e32 v243, v154, v243
	v_add_f32_e32 v243, v155, v243
	v_add_f32_e32 v243, v156, v243
	v_add_f32_e32 v243, v157, v243
	v_add_f32_e32 v243, v158, v243
	v_add_f32_e32 v243, v159, v243
	v_add_f32_e32 v196, v196, v243
	v_cvt_pk_bf16_f32 v144, v144, v145
	v_cvt_pk_bf16_f32 v145, v146, v147
	v_cvt_pk_bf16_f32 v146, v148, v149
	v_cvt_pk_bf16_f32 v147, v150, v151
	v_cvt_pk_bf16_f32 v148, v152, v153
	v_cvt_pk_bf16_f32 v149, v154, v155
	v_cvt_pk_bf16_f32 v150, v156, v157
	v_cvt_pk_bf16_f32 v151, v158, v159
	s_waitcnt lgkmcnt(7)
	v_mfma_f32_32x32x16_bf16 v[112:127], v[216:219], v[144:147], v[112:127]
	v_exp_f32_e32 v200, v200
	v_exp_f32_e32 v201, v201
	v_exp_f32_e32 v202, v202
	v_exp_f32_e32 v203, v203
	v_exp_f32_e32 v204, v204
	s_waitcnt lgkmcnt(6)
	v_mfma_f32_32x32x16_bf16 v[80:95], v[224:227], v[144:147], v[80:95]
	v_exp_f32_e32 v205, v205
	v_exp_f32_e32 v206, v206
	v_exp_f32_e32 v207, v207
	v_exp_f32_e32 v208, v208
	v_exp_f32_e32 v209, v209
	s_waitcnt lgkmcnt(5)
	v_mfma_f32_32x32x16_bf16 v[48:63], v[232:235], v[144:147], v[48:63]
	v_exp_f32_e32 v210, v210
	v_exp_f32_e32 v211, v211
	v_exp_f32_e32 v212, v212
	v_exp_f32_e32 v213, v213
	v_exp_f32_e32 v214, v214
	s_waitcnt lgkmcnt(4)
	v_mfma_f32_32x32x16_bf16 v[16:31], v[244:247], v[144:147], v[16:31]
	v_exp_f32_e32 v215, v215
	v_add_f32_e32 v243, v200, v201
	v_add_f32_e32 v243, v202, v243
	v_add_f32_e32 v243, v203, v243
	v_add_f32_e32 v243, v204, v243
	s_waitcnt lgkmcnt(3)
	v_mfma_f32_32x32x16_bf16 v[112:127], v[220:223], v[148:151], v[112:127]
	v_add_f32_e32 v243, v205, v243
	v_add_f32_e32 v243, v206, v243
	v_add_f32_e32 v243, v207, v243
	v_add_f32_e32 v243, v208, v243
	v_add_f32_e32 v243, v209, v243
	s_waitcnt lgkmcnt(2)
	v_mfma_f32_32x32x16_bf16 v[80:95], v[228:231], v[148:151], v[80:95]
	v_add_f32_e32 v243, v210, v243
	v_add_f32_e32 v243, v211, v243
	v_add_f32_e32 v243, v212, v243
	v_add_f32_e32 v243, v213, v243
	v_add_f32_e32 v243, v214, v243
	s_waitcnt lgkmcnt(1)
	v_mfma_f32_32x32x16_bf16 v[48:63], v[236:239], v[148:151], v[48:63]
	v_add_f32_e32 v243, v215, v243
	v_add_f32_e32 v197, v197, v243
	v_cvt_pk_bf16_f32 v200, v200, v201
	v_cvt_pk_bf16_f32 v201, v202, v203
	v_cvt_pk_bf16_f32 v202, v204, v205
	s_waitcnt lgkmcnt(0)
	v_mfma_f32_32x32x16_bf16 v[16:31], v[248:251], v[148:151], v[16:31]
	v_cvt_pk_bf16_f32 v203, v206, v207
	v_cvt_pk_bf16_f32 v204, v208, v209
	v_cvt_pk_bf16_f32 v205, v210, v211
	v_cvt_pk_bf16_f32 v206, v212, v213
	v_cvt_pk_bf16_f32 v207, v214, v215
	s_nop 1
	v_mfma_f32_32x32x16_bf16 v[128:143], v[216:219], v[200:203], v[128:143]
	v_mfma_f32_32x32x16_bf16 v[96:111], v[224:227], v[200:203], v[96:111]
	v_mfma_f32_32x32x16_bf16 v[64:79], v[232:235], v[200:203], v[64:79]
	v_mfma_f32_32x32x16_bf16 v[32:47], v[244:247], v[200:203], v[32:47]
	v_mfma_f32_32x32x16_bf16 v[128:143], v[220:223], v[204:207], v[128:143]
	v_mfma_f32_32x32x16_bf16 v[96:111], v[228:231], v[204:207], v[96:111]
	v_mfma_f32_32x32x16_bf16 v[64:79], v[236:239], v[204:207], v[64:79]
	v_mfma_f32_32x32x16_bf16 v[32:47], v[248:251], v[204:207], v[32:47]
	ds_read_b128 v[216:219], v199 offset:4608
	ds_read_b128 v[232:235], v193 offset:0
	ds_read_b128 v[220:223], v199 offset:4640
	ds_read_b128 v[236:239], v193 offset:32
	ds_read_b128 v[224:227], v199 offset:4672
	ds_read_b128 v[244:247], v193 offset:64
	ds_read_b128 v[228:231], v199 offset:4704
	ds_read_b128 v[248:251], v193 offset:96
	s_waitcnt lgkmcnt(6)
	v_mfma_f32_32x32x16_bf16 v[144:159], v[216:219], v[232:235], v[0:15]
	s_waitcnt lgkmcnt(4)
	v_mfma_f32_32x32x16_bf16 v[144:159], v[220:223], v[236:239], v[144:159]
	s_waitcnt lgkmcnt(2)
	v_mfma_f32_32x32x16_bf16 v[144:159], v[224:227], v[244:247], v[144:159]
	s_waitcnt lgkmcnt(0)
	v_mfma_f32_32x32x16_bf16 v[144:159], v[228:231], v[248:251], v[144:159]
	ds_read_b128 v[216:219], v199 offset:13824
	ds_read_b128 v[232:235], v193 offset:36864
	ds_read_b128 v[220:223], v199 offset:13856
	ds_read_b128 v[236:239], v193 offset:36896
	ds_read_b128 v[224:227], v199 offset:13888
	ds_read_b128 v[244:247], v193 offset:36928
	ds_read_b128 v[228:231], v199 offset:13920
	ds_read_b128 v[248:251], v193 offset:36960
	s_nop 3
	v_exp_f32_e32 v144, v144
	v_exp_f32_e32 v145, v145
	v_exp_f32_e32 v146, v146
	v_exp_f32_e32 v147, v147
	v_exp_f32_e32 v148, v148
	v_exp_f32_e32 v149, v149
	v_exp_f32_e32 v150, v150
	v_exp_f32_e32 v151, v151
	v_exp_f32_e32 v152, v152
	v_exp_f32_e32 v153, v153
	v_exp_f32_e32 v154, v154
	v_exp_f32_e32 v155, v155
	v_exp_f32_e32 v156, v156
	v_exp_f32_e32 v157, v157
	v_exp_f32_e32 v158, v158
	v_exp_f32_e32 v159, v159
	v_add_f32_e32 v243, v144, v145
	v_add_f32_e32 v243, v146, v243
	v_add_f32_e32 v243, v147, v243
	v_add_f32_e32 v243, v148, v243
	v_add_f32_e32 v243, v149, v243
	v_add_f32_e32 v243, v150, v243
	v_add_f32_e32 v243, v151, v243
	s_waitcnt lgkmcnt(6)
	v_mfma_f32_32x32x16_bf16 v[200:215], v[216:219], v[232:235], v[0:15]
	s_waitcnt lgkmcnt(4)
	v_mfma_f32_32x32x16_bf16 v[200:215], v[220:223], v[236:239], v[200:215]
	s_waitcnt lgkmcnt(2)
	v_mfma_f32_32x32x16_bf16 v[200:215], v[224:227], v[244:247], v[200:215]
	s_waitcnt lgkmcnt(0)
	v_mfma_f32_32x32x16_bf16 v[200:215], v[228:231], v[248:251], v[200:215]
	ds_read_b128 v[216:219], v198 offset:64
	ds_read_b128 v[224:227], v198 offset:4672
	ds_read_b128 v[232:235], v198 offset:9280
	ds_read_b128 v[244:247], v198 offset:13888
	ds_read_b128 v[220:223], v198 offset:96
	ds_read_b128 v[228:231], v198 offset:4704
	ds_read_b128 v[236:239], v198 offset:9312
	ds_read_b128 v[248:251], v198 offset:13920
	v_add_f32_e32 v243, v152, v243
	v_add_f32_e32 v243, v153, v243
	v_add_f32_e32 v243, v154, v243
	v_add_f32_e32 v243, v155, v243
	v_add_f32_e32 v243, v156, v243
	v_add_f32_e32 v243, v157, v243
	v_add_f32_e32 v243, v158, v243
	v_add_f32_e32 v243, v159, v243
	v_add_f32_e32 v196, v196, v243
	v_cvt_pk_bf16_f32 v144, v144, v145
	v_cvt_pk_bf16_f32 v145, v146, v147
	v_cvt_pk_bf16_f32 v146, v148, v149
	v_cvt_pk_bf16_f32 v147, v150, v151
	v_cvt_pk_bf16_f32 v148, v152, v153
	v_cvt_pk_bf16_f32 v149, v154, v155
	v_cvt_pk_bf16_f32 v150, v156, v157
	v_cvt_pk_bf16_f32 v151, v158, v159
	s_waitcnt lgkmcnt(7)
	v_mfma_f32_32x32x16_bf16 v[112:127], v[216:219], v[144:147], v[112:127]
	v_exp_f32_e32 v200, v200
	v_exp_f32_e32 v201, v201
	v_exp_f32_e32 v202, v202
	v_exp_f32_e32 v203, v203
	v_exp_f32_e32 v204, v204
	s_waitcnt lgkmcnt(6)
	v_mfma_f32_32x32x16_bf16 v[80:95], v[224:227], v[144:147], v[80:95]
	v_exp_f32_e32 v205, v205
	v_exp_f32_e32 v206, v206
	v_exp_f32_e32 v207, v207
	v_exp_f32_e32 v208, v208
	v_exp_f32_e32 v209, v209
	s_waitcnt lgkmcnt(5)
	v_mfma_f32_32x32x16_bf16 v[48:63], v[232:235], v[144:147], v[48:63]
	v_exp_f32_e32 v210, v210
	v_exp_f32_e32 v211, v211
	v_exp_f32_e32 v212, v212
	v_exp_f32_e32 v213, v213
	v_exp_f32_e32 v214, v214
	s_waitcnt lgkmcnt(4)
	v_mfma_f32_32x32x16_bf16 v[16:31], v[244:247], v[144:147], v[16:31]
	v_exp_f32_e32 v215, v215
	v_add_f32_e32 v243, v200, v201
	v_add_f32_e32 v243, v202, v243
	v_add_f32_e32 v243, v203, v243
	v_add_f32_e32 v243, v204, v243
	s_waitcnt lgkmcnt(3)
	v_mfma_f32_32x32x16_bf16 v[112:127], v[220:223], v[148:151], v[112:127]
	v_add_f32_e32 v243, v205, v243
	v_add_f32_e32 v243, v206, v243
	v_add_f32_e32 v243, v207, v243
	v_add_f32_e32 v243, v208, v243
	v_add_f32_e32 v243, v209, v243
	s_waitcnt lgkmcnt(2)
	v_mfma_f32_32x32x16_bf16 v[80:95], v[228:231], v[148:151], v[80:95]
	v_add_f32_e32 v243, v210, v243
	v_add_f32_e32 v243, v211, v243
	v_add_f32_e32 v243, v212, v243
	v_add_f32_e32 v243, v213, v243
	v_add_f32_e32 v243, v214, v243
	s_waitcnt lgkmcnt(1)
	v_mfma_f32_32x32x16_bf16 v[48:63], v[236:239], v[148:151], v[48:63]
	v_add_f32_e32 v243, v215, v243
	v_add_f32_e32 v197, v197, v243
	v_cvt_pk_bf16_f32 v200, v200, v201
	v_cvt_pk_bf16_f32 v201, v202, v203
	v_cvt_pk_bf16_f32 v202, v204, v205
	s_waitcnt lgkmcnt(0)
	v_mfma_f32_32x32x16_bf16 v[16:31], v[248:251], v[148:151], v[16:31]
	v_cvt_pk_bf16_f32 v203, v206, v207
	v_cvt_pk_bf16_f32 v204, v208, v209
	v_cvt_pk_bf16_f32 v205, v210, v211
	v_cvt_pk_bf16_f32 v206, v212, v213
	v_cvt_pk_bf16_f32 v207, v214, v215
	s_add_i32 s6, s42, 1
	s_waitcnt vmcnt(0)
	s_cmp_eq_u32 s33, 0
	s_cbranch_scc0 .Lqt_s0_1
	v_add_u32_e32 v252, 0x9000, v190
	ds_write_b128 v189, v[160:163] offset:36864
	ds_write2_b64 v252, v[164:165], v[166:167] offset1:2
	ds_write_b128 v189, v[168:171] offset:46080
	v_add_u32_e32 v252, 0xb000, v190
	ds_write2_b64 v252, v[172:173], v[174:175] offset0:128 offset1:130
	s_branch .Lqt_pf_1
.Lqt_s0_1:
	ds_write_b128 v189, v[160:163]
	ds_write2_b64 v190, v[164:165], v[166:167] offset1:2
	ds_write_b128 v189, v[168:171] offset:9216
	ds_write2_b64 v192, v[172:173], v[174:175] offset0:128 offset1:130
.Lqt_pf_1:
	s_add_i32 s10, s42, 2
	s_mov_b32 s11, 0
	s_lshl_b64 s[4:5], s[10:11], 13
	s_add_u32 s4, s50, s4
	s_addc_u32 s5, s51, s5
	s_lshl_b64 s[8:9], s[10:11], 14
	s_add_u32 s8, s52, s8
	v_lshl_add_u64 v[252:253], s[4:5], 0, v[176:177]
	s_addc_u32 s9, s53, s9
	global_load_dwordx4 v[160:163], v[252:253], off
	v_add_co_u32_e32 v252, vcc, 0x100000, v252
	v_lshl_add_u64 v[254:255], s[8:9], 0, v[176:177]
	s_nop 0
	v_addc_co_u32_e32 v253, vcc, 0, v253, vcc
	global_load_dwordx4 v[168:171], v[252:253], off
	v_add_co_u32_e32 v252, vcc, 0x2000, v254
	global_load_dwordx4 v[164:167], v[254:255], off
	s_nop 0
	v_addc_co_u32_e32 v253, vcc, 0, v255, vcc
	global_load_dwordx4 v[172:175], v[252:253], off
	v_mfma_f32_32x32x16_bf16 v[128:143], v[216:219], v[200:203], v[128:143]
	v_mfma_f32_32x32x16_bf16 v[96:111], v[224:227], v[200:203], v[96:111]
	v_mfma_f32_32x32x16_bf16 v[64:79], v[232:235], v[200:203], v[64:79]
	v_mfma_f32_32x32x16_bf16 v[32:47], v[244:247], v[200:203], v[32:47]
	v_mfma_f32_32x32x16_bf16 v[128:143], v[220:223], v[204:207], v[128:143]
	v_mfma_f32_32x32x16_bf16 v[96:111], v[228:231], v[204:207], v[96:111]
	v_mfma_f32_32x32x16_bf16 v[64:79], v[236:239], v[204:207], v[64:79]
	v_mfma_f32_32x32x16_bf16 v[32:47], v[248:251], v[204:207], v[32:47]
	s_branch .LBB0_116

.Lab_B0:
	ds_read_b128 v[216:219], v199 offset:0
	ds_read_b128 v[232:235], v193 offset:0
	ds_read_b128 v[220:223], v199 offset:32
	ds_read_b128 v[236:239], v193 offset:32
	ds_read_b128 v[224:227], v199 offset:64
	ds_read_b128 v[244:247], v193 offset:64
	ds_read_b128 v[228:231], v199 offset:96
	ds_read_b128 v[248:251], v193 offset:96
	s_waitcnt lgkmcnt(6)
	v_mfma_f32_32x32x16_bf16 v[144:159], v[216:219], v[232:235], v[0:15]
	s_waitcnt lgkmcnt(4)
	v_mfma_f32_32x32x16_bf16 v[144:159], v[220:223], v[236:239], v[144:159]
	s_waitcnt lgkmcnt(2)
	v_mfma_f32_32x32x16_bf16 v[144:159], v[224:227], v[244:247], v[144:159]
	s_waitcnt lgkmcnt(0)
	v_mfma_f32_32x32x16_bf16 v[144:159], v[228:231], v[248:251], v[144:159]
	ds_read_b128 v[216:219], v199 offset:9216
	ds_read_b128 v[232:235], v193 offset:36864
	ds_read_b128 v[220:223], v199 offset:9248
	ds_read_b128 v[236:239], v193 offset:36896
	ds_read_b128 v[224:227], v199 offset:9280
	ds_read_b128 v[244:247], v193 offset:36928
	ds_read_b128 v[228:231], v199 offset:9312
	ds_read_b128 v[248:251], v193 offset:36960
	s_nop 3
	v_exp_f32_e32 v144, v144
	v_exp_f32_e32 v145, v145
	v_exp_f32_e32 v146, v146
	v_exp_f32_e32 v147, v147
	v_exp_f32_e32 v148, v148
	v_exp_f32_e32 v149, v149
	v_exp_f32_e32 v150, v150
	v_exp_f32_e32 v151, v151
	v_exp_f32_e32 v152, v152
	v_exp_f32_e32 v153, v153
	v_exp_f32_e32 v154, v154
	v_exp_f32_e32 v155, v155
	v_exp_f32_e32 v156, v156
	v_exp_f32_e32 v157, v157
	v_exp_f32_e32 v158, v158
	v_exp_f32_e32 v159, v159
	v_add_f32_e32 v243, v144, v145
	v_add_f32_e32 v243, v146, v243
	v_add_f32_e32 v243, v147, v243
	v_add_f32_e32 v243, v148, v243
	v_add_f32_e32 v243, v149, v243
	v_add_f32_e32 v243, v150, v243
	v_add_f32_e32 v243, v151, v243
	s_waitcnt lgkmcnt(6)
	v_mfma_f32_32x32x16_bf16 v[200:215], v[216:219], v[232:235], v[0:15]
	s_waitcnt lgkmcnt(4)
	v_mfma_f32_32x32x16_bf16 v[200:215], v[220:223], v[236:239], v[200:215]
	s_waitcnt lgkmcnt(2)
	v_mfma_f32_32x32x16_bf16 v[200:215], v[224:227], v[244:247], v[200:215]
	s_waitcnt lgkmcnt(0)
	v_mfma_f32_32x32x16_bf16 v[200:215], v[228:231], v[248:251], v[200:215]
	ds_read_b128 v[216:219], v198 offset:0
	ds_read_b128 v[224:227], v198 offset:4608
	ds_read_b128 v[232:235], v198 offset:9216
	ds_read_b128 v[244:247], v198 offset:13824
	ds_read_b128 v[220:223], v198 offset:32
	ds_read_b128 v[228:231], v198 offset:4640
	ds_read_b128 v[236:239], v198 offset:9248
	ds_read_b128 v[248:251], v198 offset:13856
	v_add_f32_e32 v243, v152, v243
	v_add_f32_e32 v243, v153, v243
	v_add_f32_e32 v243, v154, v243
	v_add_f32_e32 v243, v155, v243
	v_add_f32_e32 v243, v156, v243
	v_add_f32_e32 v243, v157, v243
	v_add_f32_e32 v243, v158, v243
	v_add_f32_e32 v243, v159, v243
	v_add_f32_e32 v196, v196, v243
	v_cvt_pk_bf16_f32 v144, v144, v145
	v_cvt_pk_bf16_f32 v145, v146, v147
	v_cvt_pk_bf16_f32 v146, v148, v149
	v_cvt_pk_bf16_f32 v147, v150, v151
	v_cvt_pk_bf16_f32 v148, v152, v153
	v_cvt_pk_bf16_f32 v149, v154, v155
	v_cvt_pk_bf16_f32 v150, v156, v157
	v_cvt_pk_bf16_f32 v151, v158, v159
	s_waitcnt lgkmcnt(7)
	v_mfma_f32_32x32x16_bf16 v[112:127], v[216:219], v[144:147], v[112:127]
	v_exp_f32_e32 v200, v200
	v_exp_f32_e32 v201, v201
	v_exp_f32_e32 v202, v202
	v_exp_f32_e32 v203, v203
	v_exp_f32_e32 v204, v204
	s_waitcnt lgkmcnt(6)
	v_mfma_f32_32x32x16_bf16 v[80:95], v[224:227], v[144:147], v[80:95]
	v_exp_f32_e32 v205, v205
	v_exp_f32_e32 v206, v206
	v_exp_f32_e32 v207, v207
	v_exp_f32_e32 v208, v208
	v_exp_f32_e32 v209, v209
	s_waitcnt lgkmcnt(5)
	v_mfma_f32_32x32x16_bf16 v[48:63], v[232:235], v[144:147], v[48:63]
	v_exp_f32_e32 v210, v210
	v_exp_f32_e32 v211, v211
	v_exp_f32_e32 v212, v212
	v_exp_f32_e32 v213, v213
	v_exp_f32_e32 v214, v214
	s_waitcnt lgkmcnt(4)
	v_mfma_f32_32x32x16_bf16 v[16:31], v[244:247], v[144:147], v[16:31]
	v_exp_f32_e32 v215, v215
	v_add_f32_e32 v243, v200, v201
	v_add_f32_e32 v243, v202, v243
	v_add_f32_e32 v243, v203, v243
	v_add_f32_e32 v243, v204, v243
	s_waitcnt lgkmcnt(3)
	v_mfma_f32_32x32x16_bf16 v[112:127], v[220:223], v[148:151], v[112:127]
	v_add_f32_e32 v243, v205, v243
	v_add_f32_e32 v243, v206, v243
	v_add_f32_e32 v243, v207, v243
	v_add_f32_e32 v243, v208, v243
	v_add_f32_e32 v243, v209, v243
	s_waitcnt lgkmcnt(2)
	v_mfma_f32_32x32x16_bf16 v[80:95], v[228:231], v[148:151], v[80:95]
	v_add_f32_e32 v243, v210, v243
	v_add_f32_e32 v243, v211, v243
	v_add_f32_e32 v243, v212, v243
	v_add_f32_e32 v243, v213, v243
	v_add_f32_e32 v243, v214, v243
	s_waitcnt lgkmcnt(1)
	v_mfma_f32_32x32x16_bf16 v[48:63], v[236:239], v[148:151], v[48:63]
	v_add_f32_e32 v243, v215, v243
	v_add_f32_e32 v197, v197, v243
	v_cvt_pk_bf16_f32 v200, v200, v201
	v_cvt_pk_bf16_f32 v201, v202, v203
	v_cvt_pk_bf16_f32 v202, v204, v205
	s_waitcnt lgkmcnt(0)
	v_mfma_f32_32x32x16_bf16 v[16:31], v[248:251], v[148:151], v[16:31]
	v_cvt_pk_bf16_f32 v203, v206, v207
	v_cvt_pk_bf16_f32 v204, v208, v209
	v_cvt_pk_bf16_f32 v205, v210, v211
	v_cvt_pk_bf16_f32 v206, v212, v213
	v_cvt_pk_bf16_f32 v207, v214, v215
	s_nop 1
	v_mfma_f32_32x32x16_bf16 v[128:143], v[216:219], v[200:203], v[128:143]
	v_mfma_f32_32x32x16_bf16 v[96:111], v[224:227], v[200:203], v[96:111]
	v_mfma_f32_32x32x16_bf16 v[64:79], v[232:235], v[200:203], v[64:79]
	v_mfma_f32_32x32x16_bf16 v[32:47], v[244:247], v[200:203], v[32:47]
	v_mfma_f32_32x32x16_bf16 v[128:143], v[220:223], v[204:207], v[128:143]
	v_mfma_f32_32x32x16_bf16 v[96:111], v[228:231], v[204:207], v[96:111]
	v_mfma_f32_32x32x16_bf16 v[64:79], v[236:239], v[204:207], v[64:79]
	v_mfma_f32_32x32x16_bf16 v[32:47], v[248:251], v[204:207], v[32:47]
	ds_read_b128 v[216:219], v199 offset:4608
	ds_read_b128 v[232:235], v193 offset:0
	ds_read_b128 v[220:223], v199 offset:4640
	ds_read_b128 v[236:239], v193 offset:32
	ds_read_b128 v[224:227], v199 offset:4672
	ds_read_b128 v[244:247], v193 offset:64
	ds_read_b128 v[228:231], v199 offset:4704
	ds_read_b128 v[248:251], v193 offset:96
	s_waitcnt lgkmcnt(6)
	v_mfma_f32_32x32x16_bf16 v[144:159], v[216:219], v[232:235], v[0:15]
	s_waitcnt lgkmcnt(4)
	v_mfma_f32_32x32x16_bf16 v[144:159], v[220:223], v[236:239], v[144:159]
	s_waitcnt lgkmcnt(2)
	v_mfma_f32_32x32x16_bf16 v[144:159], v[224:227], v[244:247], v[144:159]
	s_waitcnt lgkmcnt(0)
	v_mfma_f32_32x32x16_bf16 v[144:159], v[228:231], v[248:251], v[144:159]
	ds_read_b128 v[216:219], v199 offset:13824
	ds_read_b128 v[232:235], v193 offset:36864
	ds_read_b128 v[220:223], v199 offset:13856
	ds_read_b128 v[236:239], v193 offset:36896
	ds_read_b128 v[224:227], v199 offset:13888
	ds_read_b128 v[244:247], v193 offset:36928
	ds_read_b128 v[228:231], v199 offset:13920
	ds_read_b128 v[248:251], v193 offset:36960
	s_nop 3
	v_exp_f32_e32 v144, v144
	v_exp_f32_e32 v145, v145
	v_exp_f32_e32 v146, v146
	v_exp_f32_e32 v147, v147
	v_exp_f32_e32 v148, v148
	v_exp_f32_e32 v149, v149
	v_exp_f32_e32 v150, v150
	v_exp_f32_e32 v151, v151
	v_exp_f32_e32 v152, v152
	v_exp_f32_e32 v153, v153
	v_exp_f32_e32 v154, v154
	v_exp_f32_e32 v155, v155
	v_exp_f32_e32 v156, v156
	v_exp_f32_e32 v157, v157
	v_exp_f32_e32 v158, v158
	v_exp_f32_e32 v159, v159
	v_add_f32_e32 v243, v144, v145
	v_add_f32_e32 v243, v146, v243
	v_add_f32_e32 v243, v147, v243
	v_add_f32_e32 v243, v148, v243
	v_add_f32_e32 v243, v149, v243
	v_add_f32_e32 v243, v150, v243
	v_add_f32_e32 v243, v151, v243
	s_waitcnt lgkmcnt(6)
	v_mfma_f32_32x32x16_bf16 v[200:215], v[216:219], v[232:235], v[0:15]
	s_waitcnt lgkmcnt(4)
	v_mfma_f32_32x32x16_bf16 v[200:215], v[220:223], v[236:239], v[200:215]
	s_waitcnt lgkmcnt(2)
	v_mfma_f32_32x32x16_bf16 v[200:215], v[224:227], v[244:247], v[200:215]
	s_waitcnt lgkmcnt(0)
	v_mfma_f32_32x32x16_bf16 v[200:215], v[228:231], v[248:251], v[200:215]
	ds_read_b128 v[216:219], v198 offset:64
	ds_read_b128 v[224:227], v198 offset:4672
	ds_read_b128 v[232:235], v198 offset:9280
	ds_read_b128 v[244:247], v198 offset:13888
	ds_read_b128 v[220:223], v198 offset:96
	ds_read_b128 v[228:231], v198 offset:4704
	ds_read_b128 v[236:239], v198 offset:9312
	ds_read_b128 v[248:251], v198 offset:13920
	v_add_f32_e32 v243, v152, v243
	v_add_f32_e32 v243, v153, v243
	v_add_f32_e32 v243, v154, v243
	v_add_f32_e32 v243, v155, v243
	v_add_f32_e32 v243, v156, v243
	v_add_f32_e32 v243, v157, v243
	v_add_f32_e32 v243, v158, v243
	v_add_f32_e32 v243, v159, v243
	v_add_f32_e32 v196, v196, v243
	v_cvt_pk_bf16_f32 v144, v144, v145
	v_cvt_pk_bf16_f32 v145, v146, v147
	v_cvt_pk_bf16_f32 v146, v148, v149
	v_cvt_pk_bf16_f32 v147, v150, v151
	v_cvt_pk_bf16_f32 v148, v152, v153
	v_cvt_pk_bf16_f32 v149, v154, v155
	v_cvt_pk_bf16_f32 v150, v156, v157
	v_cvt_pk_bf16_f32 v151, v158, v159
	s_waitcnt lgkmcnt(7)
	v_mfma_f32_32x32x16_bf16 v[112:127], v[216:219], v[144:147], v[112:127]
	v_exp_f32_e32 v200, v200
	v_exp_f32_e32 v201, v201
	v_exp_f32_e32 v202, v202
	v_exp_f32_e32 v203, v203
	v_exp_f32_e32 v204, v204
	s_waitcnt lgkmcnt(6)
	v_mfma_f32_32x32x16_bf16 v[80:95], v[224:227], v[144:147], v[80:95]
	v_exp_f32_e32 v205, v205
	v_exp_f32_e32 v206, v206
	v_exp_f32_e32 v207, v207
	v_exp_f32_e32 v208, v208
	v_exp_f32_e32 v209, v209
	s_waitcnt lgkmcnt(5)
	v_mfma_f32_32x32x16_bf16 v[48:63], v[232:235], v[144:147], v[48:63]
	v_exp_f32_e32 v210, v210
	v_exp_f32_e32 v211, v211
	v_exp_f32_e32 v212, v212
	v_exp_f32_e32 v213, v213
	v_exp_f32_e32 v214, v214
	s_waitcnt lgkmcnt(4)
	v_mfma_f32_32x32x16_bf16 v[16:31], v[244:247], v[144:147], v[16:31]
	v_exp_f32_e32 v215, v215
	v_add_f32_e32 v243, v200, v201
	v_add_f32_e32 v243, v202, v243
	v_add_f32_e32 v243, v203, v243
	v_add_f32_e32 v243, v204, v243
	s_waitcnt lgkmcnt(3)
	v_mfma_f32_32x32x16_bf16 v[112:127], v[220:223], v[148:151], v[112:127]
	v_add_f32_e32 v243, v205, v243
	v_add_f32_e32 v243, v206, v243
	v_add_f32_e32 v243, v207, v243
	v_add_f32_e32 v243, v208, v243
	v_add_f32_e32 v243, v209, v243
	s_waitcnt lgkmcnt(2)
	v_mfma_f32_32x32x16_bf16 v[80:95], v[228:231], v[148:151], v[80:95]
	v_add_f32_e32 v243, v210, v243
	v_add_f32_e32 v243, v211, v243
	v_add_f32_e32 v243, v212, v243
	v_add_f32_e32 v243, v213, v243
	v_add_f32_e32 v243, v214, v243
	s_waitcnt lgkmcnt(1)
	v_mfma_f32_32x32x16_bf16 v[48:63], v[236:239], v[148:151], v[48:63]
	v_add_f32_e32 v243, v215, v243
	v_add_f32_e32 v197, v197, v243
	v_cvt_pk_bf16_f32 v200, v200, v201
	v_cvt_pk_bf16_f32 v201, v202, v203
	v_cvt_pk_bf16_f32 v202, v204, v205
	s_waitcnt lgkmcnt(0)
	v_mfma_f32_32x32x16_bf16 v[16:31], v[248:251], v[148:151], v[16:31]
	v_cvt_pk_bf16_f32 v203, v206, v207
	v_cvt_pk_bf16_f32 v204, v208, v209
	v_cvt_pk_bf16_f32 v205, v210, v211
	v_cvt_pk_bf16_f32 v206, v212, v213
	v_cvt_pk_bf16_f32 v207, v214, v215
	s_add_i32 s6, s42, 1
	s_waitcnt vmcnt(0)
	s_cmp_eq_u32 s33, 0
	s_cbranch_scc0 .Lqt_s0_2
	v_add_u32_e32 v252, 0x9000, v190
	ds_write_b128 v189, v[160:163] offset:36864
	ds_write2_b64 v252, v[164:165], v[166:167] offset1:2
	ds_write_b128 v189, v[168:171] offset:46080
	v_add_u32_e32 v252, 0xb000, v190
	ds_write2_b64 v252, v[172:173], v[174:175] offset0:128 offset1:130
	s_branch .Lqt_pf_2

.Lqt_pf_2:
	s_add_i32 s10, s42, 2
	s_mov_b32 s11, 0
	s_lshl_b64 s[4:5], s[10:11], 13
	s_add_u32 s4, s50, s4
	s_addc_u32 s5, s51, s5
	s_lshl_b64 s[8:9], s[10:11], 14
	s_add_u32 s8, s52, s8
	v_lshl_add_u64 v[252:253], s[4:5], 0, v[176:177]
	s_addc_u32 s9, s53, s9
	global_load_dwordx4 v[160:163], v[252:253], off
	v_add_co_u32_e32 v252, vcc, 0x100000, v252
	v_lshl_add_u64 v[254:255], s[8:9], 0, v[176:177]
	s_nop 0
	v_addc_co_u32_e32 v253, vcc, 0, v253, vcc
	global_load_dwordx4 v[168:171], v[252:253], off
	v_add_co_u32_e32 v252, vcc, 0x2000, v254
	global_load_dwordx4 v[164:167], v[254:255], off
	s_nop 0
	v_addc_co_u32_e32 v253, vcc, 0, v255, vcc
	global_load_dwordx4 v[172:175], v[252:253], off
	s_add_i32 s4, s42, 1
	s_cmp_lt_u32 s4, s98
	s_cbranch_scc1 .LBB0_116
	s_nop 1
	v_mfma_f32_32x32x16_bf16 v[128:143], v[216:219], v[200:203], v[128:143]
	v_mfma_f32_32x32x16_bf16 v[96:111], v[224:227], v[200:203], v[96:111]
	v_mfma_f32_32x32x16_bf16 v[64:79], v[232:235], v[200:203], v[64:79]
	v_mfma_f32_32x32x16_bf16 v[32:47], v[244:247], v[200:203], v[32:47]
	v_mfma_f32_32x32x16_bf16 v[128:143], v[220:223], v[204:207], v[128:143]
	v_mfma_f32_32x32x16_bf16 v[96:111], v[228:231], v[204:207], v[96:111]
	v_mfma_f32_32x32x16_bf16 v[64:79], v[236:239], v[204:207], v[64:79]
	v_mfma_f32_32x32x16_bf16 v[32:47], v[248:251], v[204:207], v[32:47]
	s_branch .LBB0_116
